# rout state-term section software-pipelined (5 LDS reads in flight, alternating partial accumulators)
# speedup vs baseline: 1.0013x; 1.0013x over previous
; #define LAS __attribute__((address_space(3)))
; __device__ __forceinline__ f32x4 mfma16(bf16x8 a, bf16x8 b, f32x4 c) { return __builtin_amdgcn_mfma_f32_16x16x32_bf16(a, b, c, 0, 0, 0); }
; __device__ __forceinline__ void rout_item(const Args& a, int l, int it, LAS unsigned char* lds, int tid) {
;     ...
; #pragma unroll 1
;         for (int hh = 0; hh < 2; ++hh) {
;             u32x4 sreg[8];
; #pragma unroll
;             for (int i = 0; i < 8; ++i) { const int c = tid + 512 * (i + 8 * hh); sreg[i] = *(const u32x4*)(ST + (size_t)(c >> 5) * 256 + (c & 31) * 8); }
; #pragma unroll
;             for (int i = 0; i < 8; ++i) { const int c = tid + 512 * (i + 8 * hh); *(LAS u32x4*)(lds + (c >> 5) * 528 + (c & 31) * 16) = sreg[i]; }
;         }
;         __syncthreads();
;         const float sc = dir ? __expf(lgb * (float)(128 - jq)) : __expf(lgf * (float)(jq + 1));
; #pragma unroll
;         for (int dt = 0; dt < 16; ++dt) { f32x4 tacc = (f32x4){0.f, 0.f, 0.f, 0.f};
; #pragma unroll
;             for (int ks = 0; ks < 8; ++ks) tacc = mfma16(*(const LAS bf16x8*)(lds + (dt * 16 + fr) * 528 + (ks * 32 + 8 * fq) * 2), qf2[ks], tacc);
;             O[dt] += tacc * sc; }
.LBB0_331:
	v_add_u32_e32 v121, s41, v113
	v_ashrrev_i32_e32 v130, 5, v121
	v_add_u32_e32 v100, 0x200, v121
	v_cndmask_b32_e64 v96, 0, 1, s[42:43]
	v_ashrrev_i32_e32 v131, 31, v130
	v_ashrrev_i32_e32 v132, 5, v100
	v_add_u32_e32 v104, 0x400, v121
	v_cmp_ne_u32_e32 vcc, 1, v96
	v_lshlrev_b64 v[96:97], 9, v[130:131]
	v_ashrrev_i32_e32 v133, 31, v132
	v_ashrrev_i32_e32 v134, 5, v104
	v_add_u32_e32 v108, 0x600, v121
	v_lshl_add_u64 v[96:97], v[128:129], 0, v[96:97]
	v_lshlrev_b64 v[100:101], 9, v[132:133]
	v_ashrrev_i32_e32 v135, 31, v134
	v_ashrrev_i32_e32 v136, 5, v108
	v_add_u32_e32 v131, 0x800, v121
	global_load_dwordx4 v[96:99], v[96:97], off
	v_lshl_add_u64 v[100:101], v[128:129], 0, v[100:101]
	v_lshlrev_b64 v[104:105], 9, v[134:135]
	v_ashrrev_i32_e32 v137, 31, v136
	v_ashrrev_i32_e32 v252, 5, v131
	v_add_u32_e32 v131, 0xa00, v121
	global_load_dwordx4 v[100:103], v[100:101], off
	v_lshl_add_u64 v[104:105], v[128:129], 0, v[104:105]
	v_lshlrev_b64 v[108:109], 9, v[136:137]
	v_ashrrev_i32_e32 v253, 31, v252
	v_ashrrev_i32_e32 v232, 5, v131
	v_add_u32_e32 v131, 0xc00, v121
	global_load_dwordx4 v[104:107], v[104:105], off
	v_lshl_add_u64 v[108:109], v[128:129], 0, v[108:109]
	v_lshlrev_b64 v[214:215], 9, v[252:253]
	v_ashrrev_i32_e32 v233, 31, v232
	v_ashrrev_i32_e32 v234, 5, v131
	v_add_u32_e32 v121, 0xe00, v121
	global_load_dwordx4 v[108:111], v[108:109], off
	v_lshl_add_u64 v[214:215], v[128:129], 0, v[214:215]
	v_lshlrev_b64 v[218:219], 9, v[232:233]
	v_ashrrev_i32_e32 v235, 31, v234
	v_ashrrev_i32_e32 v236, 5, v121
	global_load_dwordx4 v[214:217], v[214:215], off
	v_lshl_add_u64 v[218:219], v[128:129], 0, v[218:219]
	v_lshlrev_b64 v[244:245], 9, v[234:235]
	v_ashrrev_i32_e32 v237, 31, v236
	global_load_dwordx4 v[218:221], v[218:219], off
	v_lshl_add_u64 v[244:245], v[128:129], 0, v[244:245]
	v_lshlrev_b64 v[248:249], 9, v[236:237]
	global_load_dwordx4 v[244:247], v[244:245], off
	v_lshl_add_u64 v[248:249], v[128:129], 0, v[248:249]
	global_load_dwordx4 v[248:251], v[248:249], off
	v_mad_u64_u32 v[130:131], s[14:15], v130, s68, v[112:113]
	s_movk_i32 s41, 0x1000
	s_mov_b64 s[42:43], 0
	s_and_b64 vcc, exec, vcc
	s_waitcnt vmcnt(0)
	ds_write_b128 v130, v[96:99]
	v_mad_u64_u32 v[96:97], s[14:15], v132, s68, v[112:113]
	ds_write_b128 v96, v[100:103]
	v_mad_u64_u32 v[96:97], s[14:15], v134, s68, v[112:113]
	ds_write_b128 v96, v[104:107]
	v_mad_u64_u32 v[96:97], s[14:15], v136, s68, v[112:113]
	ds_write_b128 v96, v[108:111]
	v_mad_u64_u32 v[96:97], s[14:15], v252, s68, v[112:113]
	ds_write_b128 v96, v[214:217]
	v_mad_u64_u32 v[96:97], s[14:15], v232, s68, v[112:113]
	ds_write_b128 v96, v[218:221]
	v_mad_u64_u32 v[96:97], s[14:15], v234, s68, v[112:113]
	ds_write_b128 v96, v[244:247]
	v_mad_u64_u32 v[96:97], s[14:15], v236, s68, v[112:113]
	ds_write_b128 v96, v[248:251]
	s_cbranch_vccz .LBB0_331
	s_waitcnt lgkmcnt(0)
	s_barrier
	v_cndmask_b32_e64 v96, v211, v212, s[4:5]
	ds_read_b128 v[102:105], v142
	ds_read_b128 v[214:217], v142 offset:64
	ds_read_b128 v[218:221], v142 offset:128
	ds_read_b128 v[244:247], v142 offset:192
	ds_read_b128 v[248:251], v142 offset:256
	ds_read_b128 v[232:235], v142 offset:320
	s_waitcnt lgkmcnt(5)
	v_mfma_f32_16x16x32_bf16 v[98:101], v[102:105], v[64:67], 0
	ds_read_b128 v[102:105], v142 offset:384
	s_waitcnt lgkmcnt(5)
	v_mfma_f32_16x16x32_bf16 v[98:101], v[214:217], v[68:71], v[98:101]
	ds_read_b128 v[214:217], v142 offset:448
	s_waitcnt lgkmcnt(5)
	v_mfma_f32_16x16x32_bf16 v[98:101], v[218:221], v[72:75], v[98:101]
	ds_read_b128 v[218:221], v142 offset:8448
	s_waitcnt lgkmcnt(5)
	v_mfma_f32_16x16x32_bf16 v[98:101], v[244:247], v[76:79], v[98:101]
	ds_read_b128 v[244:247], v142 offset:8512
	s_waitcnt lgkmcnt(5)
	v_mfma_f32_16x16x32_bf16 v[98:101], v[248:251], v[80:83], v[98:101]
	ds_read_b128 v[248:251], v142 offset:8576
	s_waitcnt lgkmcnt(5)
	v_mfma_f32_16x16x32_bf16 v[98:101], v[232:235], v[84:87], v[98:101]
	ds_read_b128 v[232:235], v142 offset:8640
	s_waitcnt lgkmcnt(5)
	v_mfma_f32_16x16x32_bf16 v[98:101], v[102:105], v[88:91], v[98:101]
	ds_read_b128 v[102:105], v142 offset:8704
	s_waitcnt lgkmcnt(5)
	v_mfma_f32_16x16x32_bf16 v[98:101], v[214:217], v[92:95], v[98:101]
	ds_read_b128 v[214:217], v142 offset:8768
	s_waitcnt lgkmcnt(5)
	v_mfma_f32_16x16x32_bf16 v[106:109], v[218:221], v[64:67], 0
	ds_read_b128 v[218:221], v142 offset:8832
	s_waitcnt lgkmcnt(5)
	v_mfma_f32_16x16x32_bf16 v[106:109], v[244:247], v[68:71], v[106:109]
	s_nop 1
	v_pk_fma_f32 v[16:17], v[96:97], v[98:99], v[16:17] op_sel_hi:[0,1,1]
	v_pk_fma_f32 v[18:19], v[96:97], v[100:101], v[18:19] op_sel_hi:[0,1,1]
	ds_read_b128 v[244:247], v142 offset:8896
	s_waitcnt lgkmcnt(5)
	v_mfma_f32_16x16x32_bf16 v[106:109], v[248:251], v[72:75], v[106:109]
	ds_read_b128 v[248:251], v142 offset:16896
	s_waitcnt lgkmcnt(5)
	v_mfma_f32_16x16x32_bf16 v[106:109], v[232:235], v[76:79], v[106:109]
	ds_read_b128 v[232:235], v142 offset:16960
	s_waitcnt lgkmcnt(5)
	v_mfma_f32_16x16x32_bf16 v[106:109], v[102:105], v[80:83], v[106:109]
	ds_read_b128 v[102:105], v142 offset:17024
	s_waitcnt lgkmcnt(5)
	v_mfma_f32_16x16x32_bf16 v[106:109], v[214:217], v[84:87], v[106:109]
	ds_read_b128 v[214:217], v142 offset:17088
	s_waitcnt lgkmcnt(5)
	v_mfma_f32_16x16x32_bf16 v[106:109], v[218:221], v[88:91], v[106:109]
	ds_read_b128 v[218:221], v142 offset:17152
	s_waitcnt lgkmcnt(5)
	v_mfma_f32_16x16x32_bf16 v[106:109], v[244:247], v[92:95], v[106:109]
	ds_read_b128 v[244:247], v142 offset:17216
	s_waitcnt lgkmcnt(5)
	v_mfma_f32_16x16x32_bf16 v[98:101], v[248:251], v[64:67], 0
	ds_read_b128 v[248:251], v142 offset:17280
	s_waitcnt lgkmcnt(5)
; #define LAS __attribute__((address_space(3)))
; __device__ __forceinline__ f32x4 mfma16(bf16x8 a, bf16x8 b, f32x4 c) { return __builtin_amdgcn_mfma_f32_16x16x32_bf16(a, b, c, 0, 0, 0); }
; __device__ __forceinline__ void rout_item(const Args& a, int l, int it, LAS unsigned char* lds, int tid) {
;     ...
;         const float sc = dir ? __expf(lgb * (float)(128 - jq)) : __expf(lgf * (float)(jq + 1));
; #pragma unroll
;         for (int dt = 0; dt < 16; ++dt) { f32x4 tacc = (f32x4){0.f, 0.f, 0.f, 0.f};
; #pragma unroll
;             for (int ks = 0; ks < 8; ++ks) tacc = mfma16(*(const LAS bf16x8*)(lds + (dt * 16 + fr) * 528 + (ks * 32 + 8 * fq) * 2), qf2[ks], tacc);
;             O[dt] += tacc * sc; }
	v_mfma_f32_16x16x32_bf16 v[98:101], v[232:235], v[68:71], v[98:101]
	s_nop 1
	v_pk_fma_f32 v[8:9], v[96:97], v[106:107], v[8:9] op_sel_hi:[0,1,1]
	v_pk_fma_f32 v[10:11], v[96:97], v[108:109], v[10:11] op_sel_hi:[0,1,1]
	ds_read_b128 v[232:235], v142 offset:17344
	s_waitcnt lgkmcnt(5)
	v_mfma_f32_16x16x32_bf16 v[98:101], v[102:105], v[72:75], v[98:101]
	ds_read_b128 v[102:105], v142 offset:25344
	s_waitcnt lgkmcnt(5)
	v_mfma_f32_16x16x32_bf16 v[98:101], v[214:217], v[76:79], v[98:101]
	ds_read_b128 v[214:217], v142 offset:25408
	s_waitcnt lgkmcnt(5)
	v_mfma_f32_16x16x32_bf16 v[98:101], v[218:221], v[80:83], v[98:101]
	ds_read_b128 v[218:221], v142 offset:25472
	s_waitcnt lgkmcnt(5)
	v_mfma_f32_16x16x32_bf16 v[98:101], v[244:247], v[84:87], v[98:101]
	ds_read_b128 v[244:247], v142 offset:25536
	s_waitcnt lgkmcnt(5)
	v_mfma_f32_16x16x32_bf16 v[98:101], v[248:251], v[88:91], v[98:101]
	ds_read_b128 v[248:251], v142 offset:25600
	s_waitcnt lgkmcnt(5)
	v_mfma_f32_16x16x32_bf16 v[98:101], v[232:235], v[92:95], v[98:101]
	ds_read_b128 v[232:235], v142 offset:25664
	s_waitcnt lgkmcnt(5)
	v_mfma_f32_16x16x32_bf16 v[106:109], v[102:105], v[64:67], 0
	ds_read_b128 v[102:105], v142 offset:25728
	s_waitcnt lgkmcnt(5)
	v_mfma_f32_16x16x32_bf16 v[106:109], v[214:217], v[68:71], v[106:109]
	s_nop 1
	v_pk_fma_f32 v[0:1], v[96:97], v[98:99], v[0:1] op_sel_hi:[0,1,1]
	v_pk_fma_f32 v[2:3], v[96:97], v[100:101], v[2:3] op_sel_hi:[0,1,1]
	ds_read_b128 v[214:217], v142 offset:25792
	s_waitcnt lgkmcnt(5)
	v_mfma_f32_16x16x32_bf16 v[106:109], v[218:221], v[72:75], v[106:109]
	ds_read_b128 v[218:221], v142 offset:33792
	s_waitcnt lgkmcnt(5)
	v_mfma_f32_16x16x32_bf16 v[106:109], v[244:247], v[76:79], v[106:109]
	ds_read_b128 v[244:247], v142 offset:33856
	s_waitcnt lgkmcnt(5)
	v_mfma_f32_16x16x32_bf16 v[106:109], v[248:251], v[80:83], v[106:109]
	ds_read_b128 v[248:251], v142 offset:33920
	s_waitcnt lgkmcnt(5)
	v_mfma_f32_16x16x32_bf16 v[106:109], v[232:235], v[84:87], v[106:109]
	ds_read_b128 v[232:235], v142 offset:33984
	s_waitcnt lgkmcnt(5)
	v_mfma_f32_16x16x32_bf16 v[106:109], v[102:105], v[88:91], v[106:109]
	ds_read_b128 v[102:105], v142 offset:34048
	s_waitcnt lgkmcnt(5)
	v_mfma_f32_16x16x32_bf16 v[106:109], v[214:217], v[92:95], v[106:109]
	ds_read_b128 v[214:217], v142 offset:34112
	s_waitcnt lgkmcnt(5)
	v_mfma_f32_16x16x32_bf16 v[98:101], v[218:221], v[64:67], 0
	ds_read_b128 v[218:221], v142 offset:34176
	s_waitcnt lgkmcnt(5)
	v_mfma_f32_16x16x32_bf16 v[98:101], v[244:247], v[68:71], v[98:101]
	s_nop 1
	v_pk_fma_f32 v[4:5], v[96:97], v[106:107], v[4:5] op_sel_hi:[0,1,1]
	v_pk_fma_f32 v[6:7], v[96:97], v[108:109], v[6:7] op_sel_hi:[0,1,1]
	ds_read_b128 v[244:247], v142 offset:34240
	s_waitcnt lgkmcnt(5)
	v_mfma_f32_16x16x32_bf16 v[98:101], v[248:251], v[72:75], v[98:101]
	ds_read_b128 v[248:251], v142 offset:42240
	s_waitcnt lgkmcnt(5)
	v_mfma_f32_16x16x32_bf16 v[98:101], v[232:235], v[76:79], v[98:101]
	ds_read_b128 v[232:235], v142 offset:42304
	s_waitcnt lgkmcnt(5)
	v_mfma_f32_16x16x32_bf16 v[98:101], v[102:105], v[80:83], v[98:101]
	ds_read_b128 v[102:105], v142 offset:42368
	s_waitcnt lgkmcnt(5)
	v_mfma_f32_16x16x32_bf16 v[98:101], v[214:217], v[84:87], v[98:101]
	ds_read_b128 v[214:217], v142 offset:42432
	s_waitcnt lgkmcnt(5)
	v_mfma_f32_16x16x32_bf16 v[98:101], v[218:221], v[88:91], v[98:101]
	ds_read_b128 v[218:221], v142 offset:42496
	s_waitcnt lgkmcnt(5)
	v_mfma_f32_16x16x32_bf16 v[98:101], v[244:247], v[92:95], v[98:101]
	ds_read_b128 v[244:247], v142 offset:42560
	s_waitcnt lgkmcnt(5)
	v_mfma_f32_16x16x32_bf16 v[106:109], v[248:251], v[64:67], 0
	ds_read_b128 v[248:251], v142 offset:42624
	s_waitcnt lgkmcnt(5)
	v_mfma_f32_16x16x32_bf16 v[106:109], v[232:235], v[68:71], v[106:109]
	s_nop 1
	v_pk_fma_f32 v[24:25], v[96:97], v[98:99], v[24:25] op_sel_hi:[0,1,1]
	v_pk_fma_f32 v[26:27], v[96:97], v[100:101], v[26:27] op_sel_hi:[0,1,1]
	ds_read_b128 v[232:235], v142 offset:42688
	s_waitcnt lgkmcnt(5)
	v_mfma_f32_16x16x32_bf16 v[106:109], v[102:105], v[72:75], v[106:109]
	ds_read_b128 v[102:105], v142 offset:50688
	s_waitcnt lgkmcnt(5)
	v_mfma_f32_16x16x32_bf16 v[106:109], v[214:217], v[76:79], v[106:109]
	ds_read_b128 v[214:217], v142 offset:50752
	s_waitcnt lgkmcnt(5)
	v_mfma_f32_16x16x32_bf16 v[106:109], v[218:221], v[80:83], v[106:109]
	ds_read_b128 v[218:221], v142 offset:50816
	s_waitcnt lgkmcnt(5)
	v_mfma_f32_16x16x32_bf16 v[106:109], v[244:247], v[84:87], v[106:109]
	ds_read_b128 v[244:247], v142 offset:50880
	s_waitcnt lgkmcnt(5)
	v_mfma_f32_16x16x32_bf16 v[106:109], v[248:251], v[88:91], v[106:109]
	ds_read_b128 v[248:251], v142 offset:50944
	s_waitcnt lgkmcnt(5)
	v_mfma_f32_16x16x32_bf16 v[106:109], v[232:235], v[92:95], v[106:109]
	ds_read_b128 v[232:235], v142 offset:51008
	s_waitcnt lgkmcnt(5)
	v_mfma_f32_16x16x32_bf16 v[98:101], v[102:105], v[64:67], 0
	ds_read_b128 v[102:105], v142 offset:51072
	s_waitcnt lgkmcnt(5)
	v_mfma_f32_16x16x32_bf16 v[98:101], v[214:217], v[68:71], v[98:101]
	s_nop 1
	v_pk_fma_f32 v[28:29], v[96:97], v[106:107], v[28:29] op_sel_hi:[0,1,1]
	v_pk_fma_f32 v[30:31], v[96:97], v[108:109], v[30:31] op_sel_hi:[0,1,1]
	ds_read_b128 v[214:217], v142 offset:51136
	s_waitcnt lgkmcnt(5)
	v_mfma_f32_16x16x32_bf16 v[98:101], v[218:221], v[72:75], v[98:101]
	ds_read_b128 v[218:221], v142 offset:59136
	s_waitcnt lgkmcnt(5)
	v_mfma_f32_16x16x32_bf16 v[98:101], v[244:247], v[76:79], v[98:101]
	ds_read_b128 v[244:247], v142 offset:59200
	s_waitcnt lgkmcnt(5)
	v_mfma_f32_16x16x32_bf16 v[98:101], v[248:251], v[80:83], v[98:101]
	ds_read_b128 v[248:251], v142 offset:59264
	s_waitcnt lgkmcnt(5)
; #define LAS __attribute__((address_space(3)))
; __device__ __forceinline__ f32x4 mfma16(bf16x8 a, bf16x8 b, f32x4 c) { return __builtin_amdgcn_mfma_f32_16x16x32_bf16(a, b, c, 0, 0, 0); }
; __device__ __forceinline__ void rout_item(const Args& a, int l, int it, LAS unsigned char* lds, int tid) {
;     ...
;         const float sc = dir ? __expf(lgb * (float)(128 - jq)) : __expf(lgf * (float)(jq + 1));
; #pragma unroll
;         for (int dt = 0; dt < 16; ++dt) { f32x4 tacc = (f32x4){0.f, 0.f, 0.f, 0.f};
; #pragma unroll
;             for (int ks = 0; ks < 8; ++ks) tacc = mfma16(*(const LAS bf16x8*)(lds + (dt * 16 + fr) * 528 + (ks * 32 + 8 * fq) * 2), qf2[ks], tacc);
;             O[dt] += tacc * sc; }
	v_mfma_f32_16x16x32_bf16 v[98:101], v[232:235], v[84:87], v[98:101]
	ds_read_b128 v[232:235], v142 offset:59328
	s_waitcnt lgkmcnt(5)
	v_mfma_f32_16x16x32_bf16 v[98:101], v[102:105], v[88:91], v[98:101]
	ds_read_b128 v[102:105], v142 offset:59392
	s_waitcnt lgkmcnt(5)
	v_mfma_f32_16x16x32_bf16 v[98:101], v[214:217], v[92:95], v[98:101]
	ds_read_b128 v[214:217], v142 offset:59456
	s_waitcnt lgkmcnt(5)
	v_mfma_f32_16x16x32_bf16 v[106:109], v[218:221], v[64:67], 0
	ds_read_b128 v[218:221], v142 offset:59520
	s_waitcnt lgkmcnt(5)
	v_mfma_f32_16x16x32_bf16 v[106:109], v[244:247], v[68:71], v[106:109]
	s_nop 1
	v_pk_fma_f32 v[12:13], v[96:97], v[98:99], v[12:13] op_sel_hi:[0,1,1]
	v_pk_fma_f32 v[14:15], v[96:97], v[100:101], v[14:15] op_sel_hi:[0,1,1]
	ds_read_b128 v[244:247], v142 offset:59584
	s_waitcnt lgkmcnt(5)
	v_mfma_f32_16x16x32_bf16 v[106:109], v[248:251], v[72:75], v[106:109]
	ds_read_b128 v[248:251], v143
	s_waitcnt lgkmcnt(5)
	v_mfma_f32_16x16x32_bf16 v[106:109], v[232:235], v[76:79], v[106:109]
	ds_read_b128 v[232:235], v143 offset:64
	s_waitcnt lgkmcnt(5)
	v_mfma_f32_16x16x32_bf16 v[106:109], v[102:105], v[80:83], v[106:109]
	ds_read_b128 v[102:105], v143 offset:128
	s_waitcnt lgkmcnt(5)
	v_mfma_f32_16x16x32_bf16 v[106:109], v[214:217], v[84:87], v[106:109]
	ds_read_b128 v[214:217], v143 offset:192
	s_waitcnt lgkmcnt(5)
	v_mfma_f32_16x16x32_bf16 v[106:109], v[218:221], v[88:91], v[106:109]
	ds_read_b128 v[218:221], v143 offset:256
	s_waitcnt lgkmcnt(5)
	v_mfma_f32_16x16x32_bf16 v[106:109], v[244:247], v[92:95], v[106:109]
	ds_read_b128 v[244:247], v143 offset:320
	s_waitcnt lgkmcnt(5)
	v_mfma_f32_16x16x32_bf16 v[98:101], v[248:251], v[64:67], 0
	ds_read_b128 v[248:251], v143 offset:384
	s_waitcnt lgkmcnt(5)
	v_mfma_f32_16x16x32_bf16 v[98:101], v[232:235], v[68:71], v[98:101]
	s_nop 1
	v_pk_fma_f32 v[20:21], v[96:97], v[106:107], v[20:21] op_sel_hi:[0,1,1]
	v_pk_fma_f32 v[22:23], v[96:97], v[108:109], v[22:23] op_sel_hi:[0,1,1]
	ds_read_b128 v[232:235], v143 offset:448
	s_waitcnt lgkmcnt(5)
	v_mfma_f32_16x16x32_bf16 v[98:101], v[102:105], v[72:75], v[98:101]
	ds_read_b128 v[102:105], v143 offset:8448
	s_waitcnt lgkmcnt(5)
	v_mfma_f32_16x16x32_bf16 v[98:101], v[214:217], v[76:79], v[98:101]
	ds_read_b128 v[214:217], v143 offset:8512
	s_waitcnt lgkmcnt(5)
	v_mfma_f32_16x16x32_bf16 v[98:101], v[218:221], v[80:83], v[98:101]
	ds_read_b128 v[218:221], v143 offset:8576
	s_waitcnt lgkmcnt(5)
	v_mfma_f32_16x16x32_bf16 v[98:101], v[244:247], v[84:87], v[98:101]
	ds_read_b128 v[244:247], v143 offset:8640
	s_waitcnt lgkmcnt(5)
	v_mfma_f32_16x16x32_bf16 v[98:101], v[248:251], v[88:91], v[98:101]
	ds_read_b128 v[248:251], v143 offset:8704
	s_waitcnt lgkmcnt(5)
	v_mfma_f32_16x16x32_bf16 v[98:101], v[232:235], v[92:95], v[98:101]
	ds_read_b128 v[232:235], v143 offset:8768
	s_waitcnt lgkmcnt(5)
	v_mfma_f32_16x16x32_bf16 v[106:109], v[102:105], v[64:67], 0
	ds_read_b128 v[102:105], v143 offset:8832
	s_waitcnt lgkmcnt(5)
	v_mfma_f32_16x16x32_bf16 v[106:109], v[214:217], v[68:71], v[106:109]
	s_nop 1
	v_pk_fma_f32 v[40:41], v[96:97], v[98:99], v[40:41] op_sel_hi:[0,1,1]
	v_pk_fma_f32 v[42:43], v[96:97], v[100:101], v[42:43] op_sel_hi:[0,1,1]
	ds_read_b128 v[214:217], v143 offset:8896
	s_waitcnt lgkmcnt(5)
	v_mfma_f32_16x16x32_bf16 v[106:109], v[218:221], v[72:75], v[106:109]
	ds_read_b128 v[218:221], v143 offset:16896
	s_waitcnt lgkmcnt(5)
	v_mfma_f32_16x16x32_bf16 v[106:109], v[244:247], v[76:79], v[106:109]
	ds_read_b128 v[244:247], v143 offset:16960
	s_waitcnt lgkmcnt(5)
	v_mfma_f32_16x16x32_bf16 v[106:109], v[248:251], v[80:83], v[106:109]
	ds_read_b128 v[248:251], v143 offset:17024
	s_waitcnt lgkmcnt(5)
	v_mfma_f32_16x16x32_bf16 v[106:109], v[232:235], v[84:87], v[106:109]
	ds_read_b128 v[232:235], v143 offset:17088
	s_waitcnt lgkmcnt(5)
	v_mfma_f32_16x16x32_bf16 v[106:109], v[102:105], v[88:91], v[106:109]
	ds_read_b128 v[102:105], v143 offset:17152
	s_waitcnt lgkmcnt(5)
	v_mfma_f32_16x16x32_bf16 v[106:109], v[214:217], v[92:95], v[106:109]
	ds_read_b128 v[214:217], v143 offset:17216
	s_waitcnt lgkmcnt(5)
	v_mfma_f32_16x16x32_bf16 v[98:101], v[218:221], v[64:67], 0
	ds_read_b128 v[218:221], v143 offset:17280
	s_waitcnt lgkmcnt(5)
	v_mfma_f32_16x16x32_bf16 v[98:101], v[244:247], v[68:71], v[98:101]
	s_nop 1
	v_pk_fma_f32 v[44:45], v[96:97], v[106:107], v[44:45] op_sel_hi:[0,1,1]
	v_pk_fma_f32 v[46:47], v[96:97], v[108:109], v[46:47] op_sel_hi:[0,1,1]
	ds_read_b128 v[244:247], v143 offset:17344
	s_waitcnt lgkmcnt(5)
	v_mfma_f32_16x16x32_bf16 v[98:101], v[248:251], v[72:75], v[98:101]
	ds_read_b128 v[248:251], v143 offset:25344
	s_waitcnt lgkmcnt(5)
	v_mfma_f32_16x16x32_bf16 v[98:101], v[232:235], v[76:79], v[98:101]
	ds_read_b128 v[232:235], v143 offset:25408
	s_waitcnt lgkmcnt(5)
	v_mfma_f32_16x16x32_bf16 v[98:101], v[102:105], v[80:83], v[98:101]
	ds_read_b128 v[102:105], v143 offset:25472
	s_waitcnt lgkmcnt(5)
	v_mfma_f32_16x16x32_bf16 v[98:101], v[214:217], v[84:87], v[98:101]
	ds_read_b128 v[214:217], v143 offset:25536
	s_waitcnt lgkmcnt(5)
	v_mfma_f32_16x16x32_bf16 v[98:101], v[218:221], v[88:91], v[98:101]
	ds_read_b128 v[218:221], v143 offset:25600
	s_waitcnt lgkmcnt(5)
	v_mfma_f32_16x16x32_bf16 v[98:101], v[244:247], v[92:95], v[98:101]
	ds_read_b128 v[244:247], v143 offset:25664
	s_waitcnt lgkmcnt(5)
	v_mfma_f32_16x16x32_bf16 v[106:109], v[248:251], v[64:67], 0
	ds_read_b128 v[248:251], v143 offset:25728
	s_waitcnt lgkmcnt(5)
	v_mfma_f32_16x16x32_bf16 v[106:109], v[232:235], v[68:71], v[106:109]
	s_nop 1
	v_pk_fma_f32 v[32:33], v[96:97], v[98:99], v[32:33] op_sel_hi:[0,1,1]
	v_pk_fma_f32 v[34:35], v[96:97], v[100:101], v[34:35] op_sel_hi:[0,1,1]
	ds_read_b128 v[232:235], v143 offset:25792
	s_waitcnt lgkmcnt(5)
; #define LAS __attribute__((address_space(3)))
; __device__ __forceinline__ f32x4 mfma16(bf16x8 a, bf16x8 b, f32x4 c) { return __builtin_amdgcn_mfma_f32_16x16x32_bf16(a, b, c, 0, 0, 0); }
; __device__ __forceinline__ void rout_item(const Args& a, int l, int it, LAS unsigned char* lds, int tid) {
;     ...
;         const float sc = dir ? __expf(lgb * (float)(128 - jq)) : __expf(lgf * (float)(jq + 1));
; #pragma unroll
;         for (int dt = 0; dt < 16; ++dt) { f32x4 tacc = (f32x4){0.f, 0.f, 0.f, 0.f};
; #pragma unroll
;             for (int ks = 0; ks < 8; ++ks) tacc = mfma16(*(const LAS bf16x8*)(lds + (dt * 16 + fr) * 528 + (ks * 32 + 8 * fq) * 2), qf2[ks], tacc);
;             O[dt] += tacc * sc; }
;         __syncthreads();
	v_mfma_f32_16x16x32_bf16 v[106:109], v[102:105], v[72:75], v[106:109]
	ds_read_b128 v[102:105], v143 offset:33792
	s_waitcnt lgkmcnt(5)
	v_mfma_f32_16x16x32_bf16 v[106:109], v[214:217], v[76:79], v[106:109]
	ds_read_b128 v[214:217], v143 offset:33856
	s_waitcnt lgkmcnt(5)
	v_mfma_f32_16x16x32_bf16 v[106:109], v[218:221], v[80:83], v[106:109]
	ds_read_b128 v[218:221], v143 offset:33920
	s_waitcnt lgkmcnt(5)
	v_mfma_f32_16x16x32_bf16 v[106:109], v[244:247], v[84:87], v[106:109]
	ds_read_b128 v[244:247], v143 offset:33984
	s_waitcnt lgkmcnt(5)
	v_mfma_f32_16x16x32_bf16 v[106:109], v[248:251], v[88:91], v[106:109]
	ds_read_b128 v[248:251], v143 offset:34048
	s_waitcnt lgkmcnt(5)
	v_mfma_f32_16x16x32_bf16 v[106:109], v[232:235], v[92:95], v[106:109]
	ds_read_b128 v[232:235], v143 offset:34112
	s_waitcnt lgkmcnt(5)
	v_mfma_f32_16x16x32_bf16 v[98:101], v[102:105], v[64:67], 0
	ds_read_b128 v[102:105], v143 offset:34176
	s_waitcnt lgkmcnt(5)
	v_mfma_f32_16x16x32_bf16 v[98:101], v[214:217], v[68:71], v[98:101]
	s_nop 1
	v_pk_fma_f32 v[36:37], v[96:97], v[106:107], v[36:37] op_sel_hi:[0,1,1]
	v_pk_fma_f32 v[38:39], v[96:97], v[108:109], v[38:39] op_sel_hi:[0,1,1]
	ds_read_b128 v[214:217], v143 offset:34240
	s_waitcnt lgkmcnt(5)
	v_mfma_f32_16x16x32_bf16 v[98:101], v[218:221], v[72:75], v[98:101]
	ds_read_b128 v[218:221], v143 offset:42240
	s_waitcnt lgkmcnt(5)
	v_mfma_f32_16x16x32_bf16 v[98:101], v[244:247], v[76:79], v[98:101]
	ds_read_b128 v[244:247], v143 offset:42304
	s_waitcnt lgkmcnt(5)
	v_mfma_f32_16x16x32_bf16 v[98:101], v[248:251], v[80:83], v[98:101]
	ds_read_b128 v[248:251], v143 offset:42368
	s_waitcnt lgkmcnt(5)
	v_mfma_f32_16x16x32_bf16 v[98:101], v[232:235], v[84:87], v[98:101]
	ds_read_b128 v[232:235], v143 offset:42432
	s_waitcnt lgkmcnt(5)
	v_mfma_f32_16x16x32_bf16 v[98:101], v[102:105], v[88:91], v[98:101]
	ds_read_b128 v[102:105], v143 offset:42496
	s_waitcnt lgkmcnt(5)
	v_mfma_f32_16x16x32_bf16 v[98:101], v[214:217], v[92:95], v[98:101]
	ds_read_b128 v[214:217], v143 offset:42560
	s_waitcnt lgkmcnt(5)
	v_mfma_f32_16x16x32_bf16 v[106:109], v[218:221], v[64:67], 0
	ds_read_b128 v[218:221], v143 offset:42624
	s_waitcnt lgkmcnt(5)
	v_mfma_f32_16x16x32_bf16 v[106:109], v[244:247], v[68:71], v[106:109]
	s_nop 1
	v_pk_fma_f32 v[52:53], v[96:97], v[98:99], v[52:53] op_sel_hi:[0,1,1]
	v_pk_fma_f32 v[54:55], v[96:97], v[100:101], v[54:55] op_sel_hi:[0,1,1]
	ds_read_b128 v[244:247], v143 offset:42688
	s_waitcnt lgkmcnt(5)
	v_mfma_f32_16x16x32_bf16 v[106:109], v[248:251], v[72:75], v[106:109]
	ds_read_b128 v[248:251], v143 offset:50688
	s_waitcnt lgkmcnt(5)
	v_mfma_f32_16x16x32_bf16 v[106:109], v[232:235], v[76:79], v[106:109]
	ds_read_b128 v[232:235], v143 offset:50752
	s_waitcnt lgkmcnt(5)
	v_mfma_f32_16x16x32_bf16 v[106:109], v[102:105], v[80:83], v[106:109]
	ds_read_b128 v[102:105], v143 offset:50816
	s_waitcnt lgkmcnt(5)
	v_mfma_f32_16x16x32_bf16 v[106:109], v[214:217], v[84:87], v[106:109]
	ds_read_b128 v[214:217], v143 offset:50880
	s_waitcnt lgkmcnt(5)
	v_mfma_f32_16x16x32_bf16 v[106:109], v[218:221], v[88:91], v[106:109]
	ds_read_b128 v[218:221], v143 offset:50944
	s_waitcnt lgkmcnt(5)
	v_mfma_f32_16x16x32_bf16 v[106:109], v[244:247], v[92:95], v[106:109]
	ds_read_b128 v[244:247], v143 offset:51008
	s_waitcnt lgkmcnt(5)
	v_mfma_f32_16x16x32_bf16 v[98:101], v[248:251], v[64:67], 0
	ds_read_b128 v[248:251], v143 offset:51072
	s_waitcnt lgkmcnt(5)
	v_mfma_f32_16x16x32_bf16 v[98:101], v[232:235], v[68:71], v[98:101]
	s_nop 1
	v_pk_fma_f32 v[56:57], v[96:97], v[106:107], v[56:57] op_sel_hi:[0,1,1]
	v_pk_fma_f32 v[58:59], v[96:97], v[108:109], v[58:59] op_sel_hi:[0,1,1]
	ds_read_b128 v[232:235], v143 offset:51136
	s_waitcnt lgkmcnt(5)
	v_mfma_f32_16x16x32_bf16 v[98:101], v[102:105], v[72:75], v[98:101]
	ds_read_b128 v[102:105], v143 offset:59136
	s_waitcnt lgkmcnt(5)
	v_mfma_f32_16x16x32_bf16 v[98:101], v[214:217], v[76:79], v[98:101]
	ds_read_b128 v[214:217], v143 offset:59200
	s_waitcnt lgkmcnt(5)
	v_mfma_f32_16x16x32_bf16 v[98:101], v[218:221], v[80:83], v[98:101]
	ds_read_b128 v[218:221], v143 offset:59264
	s_waitcnt lgkmcnt(5)
	v_mfma_f32_16x16x32_bf16 v[98:101], v[244:247], v[84:87], v[98:101]
	ds_read_b128 v[244:247], v143 offset:59328
	s_waitcnt lgkmcnt(5)
	v_mfma_f32_16x16x32_bf16 v[98:101], v[248:251], v[88:91], v[98:101]
	ds_read_b128 v[248:251], v143 offset:59392
	s_waitcnt lgkmcnt(5)
	v_mfma_f32_16x16x32_bf16 v[98:101], v[232:235], v[92:95], v[98:101]
	ds_read_b128 v[232:235], v143 offset:59456
	s_waitcnt lgkmcnt(5)
	v_mfma_f32_16x16x32_bf16 v[106:109], v[102:105], v[64:67], 0
	ds_read_b128 v[102:105], v143 offset:59520
	s_waitcnt lgkmcnt(5)
	v_mfma_f32_16x16x32_bf16 v[106:109], v[214:217], v[68:71], v[106:109]
	s_nop 1
	v_pk_fma_f32 v[48:49], v[96:97], v[98:99], v[48:49] op_sel_hi:[0,1,1]
	v_pk_fma_f32 v[50:51], v[96:97], v[100:101], v[50:51] op_sel_hi:[0,1,1]
	ds_read_b128 v[214:217], v143 offset:59584
	s_waitcnt lgkmcnt(5)
	v_mfma_f32_16x16x32_bf16 v[106:109], v[218:221], v[72:75], v[106:109]
	s_waitcnt lgkmcnt(4)
	v_mfma_f32_16x16x32_bf16 v[106:109], v[244:247], v[76:79], v[106:109]
	s_waitcnt lgkmcnt(3)
	v_mfma_f32_16x16x32_bf16 v[106:109], v[248:251], v[80:83], v[106:109]
	s_waitcnt lgkmcnt(2)
	v_mfma_f32_16x16x32_bf16 v[106:109], v[232:235], v[84:87], v[106:109]
	s_waitcnt lgkmcnt(1)
	v_mfma_f32_16x16x32_bf16 v[106:109], v[102:105], v[88:91], v[106:109]
	s_waitcnt lgkmcnt(0)
	s_barrier
	v_mfma_f32_16x16x32_bf16 v[106:109], v[214:217], v[92:95], v[106:109]
	s_nop 7
	v_pk_fma_f32 v[60:61], v[96:97], v[106:107], v[60:61] op_sel_hi:[0,1,1]
	v_pk_fma_f32 v[62:63], v[96:97], v[108:109], v[62:63] op_sel_hi:[0,1,1]
	s_branch .LBB0_328
